# attention: non-temporal hint on the once-read Q fragment loads (on top of the nt row-pass / out-projection ring)
# speedup vs baseline: 1.0041x; 1.0019x over previous
; __device__ __forceinline__ void attn_phase(const Params& p, LAS unsigned char* lds) {
;     ...
;         if (tid == 0) slot[0] = __hip_atomic_fetch_add(ctr, 1u, __ATOMIC_RELAXED, __HIP_MEMORY_SCOPE_AGENT);
;         __syncthreads();
;         const int item = (int)slot[0];
;         if (item >= 1024) break;
;         const int b = item >> 7, h = (item >> 4) & 7, r0 = (item & 15) * 2, R0 = min(max(r0 - 4, 0), 24);
;         const int r = r0 + ri, rs = min(max(r - 4, 0), 24), j0 = rs - R0;
;         const int tq = b * SEQ + r * 64 + q0 + fr;
;         const bf16_t* qp = QH + ((size_t)(b * 8 + h) * SEQ + r * 64 + q0 + fr) * 64 + fq * 8;
;         const bf16x8 qf0 = *(const bf16x8*)qp, qf1 = *(const bf16x8*)(qp + 32);
;         for (int u = tid; u < 465; u += NTHREADS) rp[u] = p.rpb[h * 465 + u] * 1.4426950408889634f;
.LBB0_342:
	s_or_b64 exec, exec, s[20:21]
	v_mov_b32_e32 v0, s33
	s_waitcnt lgkmcnt(0)
	s_barrier
	ds_read_b32 v0, v0
	s_mov_b64 s[20:21], -1
	s_waitcnt lgkmcnt(0)
	v_cmp_lt_i32_e32 vcc, s40, v0
	v_readfirstlane_b32 s16, v0
	s_cbranch_vccnz .LBB0_337
	s_ashr_i32 s43, s16, 7
	s_bfe_u32 s42, s16, 0x30004
	s_lshl_b32 s16, s16, 1
	s_lshl_b32 s20, s43, 3
	s_and_b32 s16, s16, 30
	s_or_b32 s20, s20, s42
	s_add_i32 s45, s16, s10
	s_ashr_i32 s21, s20, 31
	s_lshl_b32 s44, s45, 6
	s_lshl_b64 s[26:27], s[20:21], 11
	s_add_u32 s21, s26, s44
	s_addc_u32 s38, s27, 0
	v_mov_b32_e32 v1, s38
	v_or_b32_e32 v0, s21, v28
	v_lshlrev_b64 v[0:1], 7, v[0:1]
	v_lshl_add_u64 v[0:1], v[32:33], 0, v[0:1]
	global_load_dwordx4 v[12:15], v[0:1], off nt
	global_load_dwordx4 v[4:7], v[0:1], off offset:64 nt
	s_and_saveexec_b64 s[38:39], s[0:1]
	s_cbranch_execz .LBB0_345
	s_mul_i32 s21, s42, 0x1d1
	v_add_lshl_u32 v0, s21, v170, 2
	global_load_dword v241, v0, s[50:51]
